# combined: expfirst + epilogue subw de-serialisation + loop-edge rotation + V-before-K fragment read order
# baseline (speedup 1.0000x reference)
.LBB0_641:
	s_add_i32 s24, s23, -7
	s_lshl_b32 s92, s24, 13
	s_add_u32 vcc_lo, s100, s92
	s_addc_u32 vcc_hi, s101, 0
	global_load_dwordx4 v[52:55], v248, vcc
	s_add_i32 s24, s23, -8
	s_lshl_b32 s92, s24, 7
	s_add_u32 vcc_lo, s98, s92
	s_addc_u32 vcc_hi, s99, 0
	global_load_dwordx4 v[56:59], v249, vcc
	s_mul_i32 s26, s25, 0x2400
	s_add_i32 s24, s23, -7
	s_add_i32 s27, s26, 0xffffdc00
	s_cmp_lg_u32 s25, 0
	s_cselect_b32 s27, s27, 0x9000
	v_add_u32_e32 v1, s27, v163
	ds_read_b128 v[60:63], v1 offset:36864
	ds_read_b128 v[114:117], v1 offset:36896
	ds_read_b128 v[118:121], v1 offset:41472
	ds_read_b128 v[134:137], v1 offset:41504
	ds_read_b128 v[146:149], v1 offset:36928
	ds_read_b128 v[150:153], v1 offset:36960
	ds_read_b128 v[196:199], v1 offset:41536
	ds_read_b128 v[200:203], v1 offset:41568
	s_setprio 3
	v_cvt_pk_bf16_f32 v204, v102, v103
	v_cvt_pk_bf16_f32 v205, v104, v105
	v_cvt_pk_bf16_f32 v206, v98, v99
	v_cvt_pk_bf16_f32 v207, v100, v101
	s_waitcnt lgkmcnt(7)
	s_nop 0
	v_mfma_f32_32x32x16_bf16 v[18:33], v[60:63], v[204:207], v[18:33]
	v_add_f32_e32 v1, v102, v103
	v_add_f32_e32 v1, v1, v104
	v_add_f32_e32 v1, v1, v105
	s_waitcnt lgkmcnt(5)
	v_mfma_f32_32x32x16_bf16 v[2:17], v[118:121], v[204:207], v[2:17]
	v_cvt_pk_bf16_f32 v60, v194, v187
	v_cvt_pk_bf16_f32 v61, v186, v185
	v_cvt_pk_bf16_f32 v62, v133, v132
	v_cvt_pk_bf16_f32 v63, v131, v130
	v_add_f32_e32 v1, v1, v98
	v_add_f32_e32 v1, v1, v99
	v_add_f32_e32 v1, v1, v100
	v_add_f32_e32 v1, v1, v101
	s_nop 0
	v_mfma_f32_32x32x16_bf16 v[18:33], v[114:117], v[60:63], v[18:33]
	v_add_f32_e32 v1, v1, v194
	v_add_f32_e32 v1, v1, v187
	v_add_f32_e32 v1, v1, v186
	v_add_f32_e32 v1, v1, v185
	s_waitcnt lgkmcnt(4)
	v_mfma_f32_32x32x16_bf16 v[2:17], v[134:137], v[60:63], v[2:17]
	v_cvt_pk_bf16_f32 v98, v129, v128
	v_cvt_pk_bf16_f32 v99, v127, v126
	v_cvt_pk_bf16_f32 v100, v125, v124
	v_cvt_pk_bf16_f32 v101, v123, v122
	v_add_f32_e32 v1, v1, v133
	v_add_f32_e32 v1, v1, v132
	v_add_f32_e32 v1, v1, v131
	v_add_f32_e32 v1, v1, v130
	s_waitcnt lgkmcnt(3)
	v_mfma_f32_32x32x16_bf16 v[18:33], v[146:149], v[98:101], v[18:33]
	v_add_f32_e32 v1, v1, v129
	v_add_f32_e32 v1, v1, v128
	v_add_f32_e32 v1, v1, v127
	v_add_f32_e32 v1, v1, v126
	s_waitcnt lgkmcnt(1)
	v_mfma_f32_32x32x16_bf16 v[2:17], v[196:199], v[98:101], v[2:17]
	v_cvt_pk_bf16_f32 v60, v109, v108
	v_cvt_pk_bf16_f32 v61, v107, v106
	v_cvt_pk_bf16_f32 v62, v113, v112
	v_cvt_pk_bf16_f32 v63, v111, v110
	v_add_f32_e32 v1, v1, v125
	v_add_f32_e32 v1, v1, v124
	v_add_f32_e32 v1, v1, v123
	v_add_f32_e32 v1, v1, v122
	s_nop 0
	v_mfma_f32_32x32x16_bf16 v[18:33], v[150:153], v[60:63], v[18:33]
	v_add_f32_e32 v1, v1, v109
	v_add_f32_e32 v1, v1, v108
	v_add_f32_e32 v1, v1, v107
	v_add_f32_e32 v1, v1, v106
	s_waitcnt lgkmcnt(0)
	v_mfma_f32_32x32x16_bf16 v[2:17], v[200:203], v[60:63], v[2:17]
	v_add_f32_e32 v1, v1, v113
	v_add_f32_e32 v1, v1, v112
	v_add_f32_e32 v1, v1, v111
	v_add_f32_e32 v1, v1, v110
	s_setprio 2
	s_waitcnt lgkmcnt(0)
	s_barrier
	ds_read_b128 v[240:243], v165 offset:18432
	ds_read_b128 v[244:247], v165 offset:23040
	ds_read_b128 v[130:133], v165 offset:18464
	ds_read_b128 v[146:149], v165 offset:23072
	v_exp_f32_e32 v185, v82
	v_exp_f32_e32 v186, v83
	v_exp_f32_e32 v187, v84
	v_exp_f32_e32 v194, v85
	v_exp_f32_e32 v195, v86
	v_exp_f32_e32 v196, v87
	v_exp_f32_e32 v197, v88
	v_exp_f32_e32 v198, v89
	s_waitcnt lgkmcnt(2)
	v_mfma_f32_32x32x16_bf16 v[114:129], v[240:243], v[158:161], v[34:49]
	s_waitcnt lgkmcnt(1)
	v_mfma_f32_32x32x16_bf16 v[98:113], v[244:247], v[158:161], v[34:49]
	v_exp_f32_e32 v199, v90
	v_exp_f32_e32 v200, v91
	v_exp_f32_e32 v201, v92
	v_exp_f32_e32 v202, v93
	v_exp_f32_e32 v134, v94
	v_exp_f32_e32 v135, v95
	v_exp_f32_e32 v136, v96
	v_exp_f32_e32 v137, v97
	v_mfma_f32_32x32x16_bf16 v[114:129], v[130:133], v[154:157], v[114:129]
	v_exp_f32_e32 v96, v66
	v_exp_f32_e32 v97, v67
	v_exp_f32_e32 v203, v68
	v_exp_f32_e32 v204, v69
	v_exp_f32_e32 v130, v70
	v_exp_f32_e32 v131, v71
	v_exp_f32_e32 v132, v72
	v_exp_f32_e32 v133, v73
	s_waitcnt lgkmcnt(0)
	v_mfma_f32_32x32x16_bf16 v[98:113], v[146:149], v[154:157], v[98:113]
	v_exp_f32_e32 v205, v74
	v_exp_f32_e32 v206, v75
	v_exp_f32_e32 v207, v76
	v_exp_f32_e32 v208, v77
	v_exp_f32_e32 v209, v78
	v_exp_f32_e32 v210, v79
	v_exp_f32_e32 v211, v80
	v_exp_f32_e32 v212, v81
	v_add_u32_e32 v88, s26, v163
	ds_read_b128 v[60:63], v88 offset:41472
	ds_read_b128 v[64:67], v88 offset:36864
	ds_read_b128 v[68:71], v88 offset:36896
	ds_read_b128 v[72:75], v88 offset:41504
	ds_read_b128 v[76:79], v88 offset:36928
	ds_read_b128 v[80:83], v88 offset:41536
	ds_read_b128 v[84:87], v88 offset:36960
	ds_read_b128 v[88:91], v88 offset:41568
	ds_read_b128 v[240:243], v165 offset:27648
	ds_read_b128 v[244:247], v165 offset:32256
	s_cmp_gt_i32 s25, 2
	s_cselect_b32 s27, -3, 2
	s_add_i32 s27, s27, s25
	s_add_i32 s26, s23, -6
	s_mulk_i32 s27, 0x2400
	s_min_u32 s26, s26, s13
	v_add_u32_e32 v51, s27, v182
	s_min_u32 s24, s24, s13
	s_lshl_b32 s92, s26, 13
	s_waitcnt vmcnt(3)
	ds_write_b128 v182, v[138:141]
	s_waitcnt vmcnt(2)
	ds_write_b128 v51, v[142:145] offset:36864
	v_add_f32_e32 v1, v50, v1
	s_add_u32 vcc_lo, s100, s92
	s_addc_u32 vcc_hi, s101, 0
	global_load_dwordx4 v[146:149], v248, vcc
	s_lshl_b32 s92, s24, 7
	s_add_u32 vcc_lo, s98, s92
	s_addc_u32 vcc_hi, s99, 0
	global_load_dwordx4 v[150:153], v249, vcc
	s_add_i32 s27, s25, 1
	s_setprio 1
	v_cvt_pk_bf16_f32 v92, v185, v186
	v_cvt_pk_bf16_f32 v93, v187, v194
	v_cvt_pk_bf16_f32 v94, v195, v196
	v_cvt_pk_bf16_f32 v95, v197, v198
	s_waitcnt lgkmcnt(10)
	s_nop 0
	v_mfma_f32_32x32x16_bf16 v[18:33], v[64:67], v[92:95], v[18:33]
	v_add_f32_e32 v213, v185, v186
	v_add_f32_e32 v213, v213, v187
	v_add_f32_e32 v213, v213, v194
	s_nop 0
	v_mfma_f32_32x32x16_bf16 v[2:17], v[60:63], v[92:95], v[2:17]
	v_cvt_pk_bf16_f32 v64, v199, v200
	v_cvt_pk_bf16_f32 v65, v201, v202
	v_cvt_pk_bf16_f32 v66, v134, v135
	v_cvt_pk_bf16_f32 v67, v136, v137
	v_add_f32_e32 v213, v213, v195
	v_add_f32_e32 v213, v213, v196
	v_add_f32_e32 v213, v213, v197
	v_add_f32_e32 v213, v213, v198
	s_waitcnt lgkmcnt(9)
	v_mfma_f32_32x32x16_bf16 v[18:33], v[68:71], v[64:67], v[18:33]
	v_add_f32_e32 v213, v213, v199
	v_add_f32_e32 v213, v213, v200
	v_add_f32_e32 v213, v213, v201
	v_add_f32_e32 v213, v213, v202
	s_waitcnt lgkmcnt(8)
	v_mfma_f32_32x32x16_bf16 v[2:17], v[72:75], v[64:67], v[2:17]
	v_cvt_pk_bf16_f32 v60, v96, v97
	v_cvt_pk_bf16_f32 v61, v203, v204
	v_cvt_pk_bf16_f32 v62, v130, v131
	v_cvt_pk_bf16_f32 v63, v132, v133
	v_add_f32_e32 v213, v213, v134
	v_add_f32_e32 v213, v213, v135
	v_add_f32_e32 v213, v213, v136
	v_add_f32_e32 v213, v213, v137
	s_waitcnt lgkmcnt(7)
	v_mfma_f32_32x32x16_bf16 v[18:33], v[76:79], v[60:63], v[18:33]
	v_add_f32_e32 v213, v213, v96
	v_add_f32_e32 v213, v213, v97
	v_add_f32_e32 v213, v213, v203
	v_add_f32_e32 v213, v213, v204
	s_waitcnt lgkmcnt(6)
	v_mfma_f32_32x32x16_bf16 v[2:17], v[80:83], v[60:63], v[2:17]
	v_cvt_pk_bf16_f32 v64, v205, v206
	v_cvt_pk_bf16_f32 v65, v207, v208
	v_cvt_pk_bf16_f32 v66, v209, v210
	v_cvt_pk_bf16_f32 v67, v211, v212
	v_add_f32_e32 v213, v213, v130
	v_add_f32_e32 v213, v213, v131
	v_add_f32_e32 v213, v213, v132
	v_add_f32_e32 v213, v213, v133
	s_waitcnt lgkmcnt(5)
	v_mfma_f32_32x32x16_bf16 v[18:33], v[84:87], v[64:67], v[18:33]
	v_add_f32_e32 v213, v213, v205
	v_add_f32_e32 v213, v213, v206
	v_add_f32_e32 v213, v213, v207
	v_add_f32_e32 v213, v213, v208
	s_waitcnt lgkmcnt(4)
	v_mfma_f32_32x32x16_bf16 v[2:17], v[88:91], v[64:67], v[2:17]
	v_add_f32_e32 v213, v213, v209
	v_add_f32_e32 v213, v213, v210
	v_add_f32_e32 v213, v213, v211
	v_add_f32_e32 v213, v213, v212
	s_setprio 0
	ds_read_b128 v[64:67], v165 offset:27680
	ds_read_b128 v[72:75], v165 offset:32288
	s_cmp_lg_u32 s25, 4
	s_cselect_b32 s24, s27, 0
	s_waitcnt lgkmcnt(2)
	v_mfma_f32_32x32x16_bf16 v[130:145], v[240:243], v[158:161], v[34:49]
	v_exp_f32_e32 v185, v114
	v_exp_f32_e32 v186, v115
	v_exp_f32_e32 v187, v116
	v_exp_f32_e32 v194, v117
	v_exp_f32_e32 v195, v118
	v_exp_f32_e32 v196, v119
	v_exp_f32_e32 v197, v120
	v_exp_f32_e32 v198, v121
	s_waitcnt lgkmcnt(1)
	v_mfma_f32_32x32x16_bf16 v[82:97], v[244:247], v[158:161], v[34:49]
	v_exp_f32_e32 v199, v122
	v_exp_f32_e32 v200, v123
	v_exp_f32_e32 v201, v124
	v_exp_f32_e32 v202, v125
	v_exp_f32_e32 v122, v126
	v_exp_f32_e32 v123, v127
	v_exp_f32_e32 v124, v128
	v_exp_f32_e32 v125, v129
	v_mfma_f32_32x32x16_bf16 v[130:145], v[64:67], v[154:157], v[130:145]
	v_exp_f32_e32 v126, v98
	v_exp_f32_e32 v127, v99
	v_exp_f32_e32 v128, v100
	v_exp_f32_e32 v129, v101
	v_exp_f32_e32 v203, v102
	v_exp_f32_e32 v204, v103
	v_exp_f32_e32 v205, v104
	v_exp_f32_e32 v206, v105
	s_waitcnt lgkmcnt(0)
	v_mfma_f32_32x32x16_bf16 v[82:97], v[72:75], v[154:157], v[82:97]
	v_exp_f32_e32 v102, v106
	v_exp_f32_e32 v103, v107
	v_exp_f32_e32 v104, v108
	v_exp_f32_e32 v105, v109
	v_exp_f32_e32 v106, v110
	v_exp_f32_e32 v107, v111
	v_exp_f32_e32 v108, v112
	v_exp_f32_e32 v109, v113
	s_cmp_gt_i32 s24, 2
	s_cselect_b32 s25, -3, 2
	s_add_i32 s25, s25, s24
	s_mulk_i32 s25, 0x2400
	v_add_u32_e32 v50, s25, v182
	s_add_i32 s25, s24, 1
	s_cmp_lg_u32 s24, 4
	s_cselect_b32 s24, s25, 0
	s_add_i32 s25, s23, -5
	s_min_u32 s25, s25, s13
	s_lshl_b32 s92, s25, 13
	s_waitcnt vmcnt(3)
	ds_write_b128 v182, v[52:55] offset:9216
	s_waitcnt vmcnt(2)
	ds_write_b128 v50, v[56:59] offset:36864
	s_add_u32 vcc_lo, s100, s92
	s_addc_u32 vcc_hi, s101, 0
	global_load_dwordx4 v[118:121], v248, vcc
	s_lshl_b32 s92, s26, 7
	s_add_u32 vcc_lo, s98, s92
	s_addc_u32 vcc_hi, s99, 0
	global_load_dwordx4 v[114:117], v249, vcc
	s_mul_i32 s26, s24, 0x2400
	s_add_i32 s27, s26, 0xffffdc00
	s_cmp_lg_u32 s24, 0
	s_cselect_b32 s27, s27, 0x9000
	v_add_u32_e32 v78, s27, v163
	ds_read_b128 v[50:53], v78 offset:36864
	ds_read_b128 v[54:57], v78 offset:36896
	ds_read_b128 v[58:61], v78 offset:41472
	ds_read_b128 v[62:65], v78 offset:41504
	ds_read_b128 v[66:69], v78 offset:36928
	ds_read_b128 v[70:73], v78 offset:36960
	ds_read_b128 v[74:77], v78 offset:41536
	ds_read_b128 v[78:81], v78 offset:41568
	s_setprio 3
	v_cvt_pk_bf16_f32 v98, v185, v186
	v_cvt_pk_bf16_f32 v99, v187, v194
	v_cvt_pk_bf16_f32 v100, v195, v196
	v_cvt_pk_bf16_f32 v101, v197, v198
	s_waitcnt lgkmcnt(7)
	s_nop 0
	v_mfma_f32_32x32x16_bf16 v[18:33], v[50:53], v[98:101], v[18:33]
	v_add_f32_e32 v110, v185, v186
	v_add_f32_e32 v110, v110, v187
	v_add_f32_e32 v110, v110, v194
	s_waitcnt lgkmcnt(5)
	v_mfma_f32_32x32x16_bf16 v[2:17], v[58:61], v[98:101], v[2:17]
	v_cvt_pk_bf16_f32 v50, v199, v200
	v_cvt_pk_bf16_f32 v51, v201, v202
	v_cvt_pk_bf16_f32 v52, v122, v123
	v_cvt_pk_bf16_f32 v53, v124, v125
	v_add_f32_e32 v110, v110, v195
	v_add_f32_e32 v110, v110, v196
	v_add_f32_e32 v110, v110, v197
	v_add_f32_e32 v110, v110, v198
	s_nop 0
	v_mfma_f32_32x32x16_bf16 v[18:33], v[54:57], v[50:53], v[18:33]
	v_add_f32_e32 v110, v110, v199
	v_add_f32_e32 v110, v110, v200
	v_add_f32_e32 v110, v110, v201
	v_add_f32_e32 v110, v110, v202
	s_waitcnt lgkmcnt(4)
	v_mfma_f32_32x32x16_bf16 v[2:17], v[62:65], v[50:53], v[2:17]
	v_cvt_pk_bf16_f32 v54, v126, v127
	v_cvt_pk_bf16_f32 v55, v128, v129
	v_cvt_pk_bf16_f32 v56, v203, v204
	v_cvt_pk_bf16_f32 v57, v205, v206
	v_add_f32_e32 v110, v110, v122
	v_add_f32_e32 v110, v110, v123
	v_add_f32_e32 v110, v110, v124
	v_add_f32_e32 v110, v110, v125
	s_waitcnt lgkmcnt(3)
	v_mfma_f32_32x32x16_bf16 v[18:33], v[66:69], v[54:57], v[18:33]
	v_add_f32_e32 v110, v110, v126
	v_add_f32_e32 v110, v110, v127
	v_add_f32_e32 v110, v110, v128
	v_add_f32_e32 v110, v110, v129
	s_waitcnt lgkmcnt(1)
	v_mfma_f32_32x32x16_bf16 v[2:17], v[74:77], v[54:57], v[2:17]
	v_cvt_pk_bf16_f32 v50, v102, v103
	v_cvt_pk_bf16_f32 v51, v104, v105
	v_cvt_pk_bf16_f32 v52, v106, v107
	v_cvt_pk_bf16_f32 v53, v108, v109
	v_add_f32_e32 v110, v110, v203
	v_add_f32_e32 v110, v110, v204
	v_add_f32_e32 v110, v110, v205
	v_add_f32_e32 v110, v110, v206
	s_nop 0
	v_mfma_f32_32x32x16_bf16 v[18:33], v[70:73], v[50:53], v[18:33]
	v_add_f32_e32 v110, v110, v102
	v_add_f32_e32 v110, v110, v103
	v_add_f32_e32 v110, v110, v104
	v_add_f32_e32 v110, v110, v105
	s_waitcnt lgkmcnt(0)
	v_mfma_f32_32x32x16_bf16 v[2:17], v[78:81], v[50:53], v[2:17]
	v_add_f32_e32 v110, v110, v106
	v_add_f32_e32 v110, v110, v107
	v_add_f32_e32 v110, v110, v108
	v_add_f32_e32 v110, v110, v109
	s_setprio 2
	s_waitcnt lgkmcnt(0)
	s_barrier
	ds_read_b128 v[240:243], v165
	ds_read_b128 v[244:247], v165 offset:4608
	ds_read_b128 v[102:105], v165 offset:32
	ds_read_b128 v[106:109], v165 offset:4640
	v_add_f32_e32 v1, v1, v213
	v_exp_f32_e32 v185, v130
	v_exp_f32_e32 v186, v131
	v_exp_f32_e32 v187, v132
	v_exp_f32_e32 v194, v133
	v_exp_f32_e32 v195, v134
	v_exp_f32_e32 v196, v135
	v_exp_f32_e32 v197, v136
	v_exp_f32_e32 v198, v137
	s_waitcnt lgkmcnt(2)
	v_mfma_f32_32x32x16_bf16 v[66:81], v[240:243], v[158:161], v[34:49]
	v_mfma_f32_32x32x16_bf16 v[50:65], v[244:247], v[158:161], v[34:49]
	v_exp_f32_e32 v134, v138
	v_exp_f32_e32 v135, v139
	v_exp_f32_e32 v136, v140
	v_exp_f32_e32 v137, v141
	v_exp_f32_e32 v138, v142
	v_exp_f32_e32 v139, v143
	v_exp_f32_e32 v140, v144
	v_exp_f32_e32 v141, v145
	s_waitcnt lgkmcnt(1)
	v_mfma_f32_32x32x16_bf16 v[66:81], v[102:105], v[154:157], v[66:81]
	v_exp_f32_e32 v142, v82
	v_exp_f32_e32 v143, v83
	v_exp_f32_e32 v144, v84
	v_exp_f32_e32 v145, v85
	v_exp_f32_e32 v199, v86
	v_exp_f32_e32 v200, v87
	v_exp_f32_e32 v201, v88
	v_exp_f32_e32 v202, v89
	s_waitcnt lgkmcnt(0)
	v_mfma_f32_32x32x16_bf16 v[50:65], v[106:109], v[154:157], v[50:65]
	v_exp_f32_e32 v203, v90
	v_exp_f32_e32 v204, v91
	v_exp_f32_e32 v205, v92
	v_exp_f32_e32 v206, v93
	v_exp_f32_e32 v207, v94
	v_exp_f32_e32 v208, v95
	v_exp_f32_e32 v209, v96
	v_exp_f32_e32 v210, v97
	v_add_f32_e32 v1, v1, v110
	v_add_u32_e32 v111, s26, v163
	ds_read_b128 v[82:85], v111 offset:41472
	ds_read_b128 v[86:89], v111 offset:36864
	ds_read_b128 v[90:93], v111 offset:36896
	ds_read_b128 v[94:97], v111 offset:41504
	ds_read_b128 v[98:101], v111 offset:36928
	ds_read_b128 v[102:105], v111 offset:41536
	ds_read_b128 v[106:109], v111 offset:36960
	ds_read_b128 v[110:113], v111 offset:41568
	ds_read_b128 v[240:243], v165 offset:9216
	ds_read_b128 v[244:247], v165 offset:13824
	s_cmp_gt_i32 s24, 2
	s_cselect_b32 s27, -3, 2
	s_add_i32 s27, s27, s24
	s_mulk_i32 s27, 0x2400
	v_add_u32_e32 v250, s27, v182
	s_mov_b32 s27, 0x18950000
	s_waitcnt vmcnt(3)
	ds_write_b128 v182, v[146:149] offset:18432
	s_waitcnt vmcnt(2)
	ds_write_b128 v250, v[150:153] offset:36864
	s_add_i32 s92, s23, -4
	s_lshl_b32 s92, s92, 13
	s_add_u32 vcc_lo, s100, s92
	s_addc_u32 vcc_hi, s101, 0
	global_load_dwordx4 v[126:129], v248, vcc
	s_lshl_b32 s92, s25, 7
	s_add_u32 vcc_lo, s98, s92
	s_addc_u32 vcc_hi, s99, 0
	global_load_dwordx4 v[122:125], v249, vcc
	s_add_i32 s26, s24, 1
	s_setprio 1
	v_cvt_pk_bf16_f32 v130, v185, v186
	v_cvt_pk_bf16_f32 v131, v187, v194
	v_cvt_pk_bf16_f32 v132, v195, v196
	v_cvt_pk_bf16_f32 v133, v197, v198
	s_waitcnt lgkmcnt(10)
	s_nop 0
	v_mfma_f32_32x32x16_bf16 v[18:33], v[86:89], v[130:133], v[18:33]
	v_add_f32_e32 v146, v185, v186
	v_add_f32_e32 v146, v146, v187
	v_add_f32_e32 v146, v146, v194
	s_nop 0
	v_mfma_f32_32x32x16_bf16 v[2:17], v[82:85], v[130:133], v[2:17]
	v_cvt_pk_bf16_f32 v86, v134, v135
	v_cvt_pk_bf16_f32 v87, v136, v137
	v_cvt_pk_bf16_f32 v88, v138, v139
	v_cvt_pk_bf16_f32 v89, v140, v141
	v_add_f32_e32 v146, v146, v195
	v_add_f32_e32 v146, v146, v196
	v_add_f32_e32 v146, v146, v197
	v_add_f32_e32 v146, v146, v198
	s_waitcnt lgkmcnt(9)
	v_mfma_f32_32x32x16_bf16 v[18:33], v[90:93], v[86:89], v[18:33]
	v_add_f32_e32 v146, v146, v134
	v_add_f32_e32 v146, v146, v135
	v_add_f32_e32 v146, v146, v136
	v_add_f32_e32 v146, v146, v137
	s_waitcnt lgkmcnt(8)
	v_mfma_f32_32x32x16_bf16 v[2:17], v[94:97], v[86:89], v[2:17]
	v_cvt_pk_bf16_f32 v82, v142, v143
	v_cvt_pk_bf16_f32 v83, v144, v145
	v_cvt_pk_bf16_f32 v84, v199, v200
	v_cvt_pk_bf16_f32 v85, v201, v202
	v_add_f32_e32 v146, v146, v138
	v_add_f32_e32 v146, v146, v139
	v_add_f32_e32 v146, v146, v140
	v_add_f32_e32 v146, v146, v141
	s_waitcnt lgkmcnt(7)
	v_mfma_f32_32x32x16_bf16 v[18:33], v[98:101], v[82:85], v[18:33]
	v_add_f32_e32 v146, v146, v142
	v_add_f32_e32 v146, v146, v143
	v_add_f32_e32 v146, v146, v144
	v_add_f32_e32 v146, v146, v145
	s_waitcnt lgkmcnt(6)
	v_mfma_f32_32x32x16_bf16 v[2:17], v[102:105], v[82:85], v[2:17]
	v_cvt_pk_bf16_f32 v86, v203, v204
	v_cvt_pk_bf16_f32 v87, v205, v206
	v_cvt_pk_bf16_f32 v88, v207, v208
	v_cvt_pk_bf16_f32 v89, v209, v210
	v_add_f32_e32 v146, v146, v199
	v_add_f32_e32 v146, v146, v200
	v_add_f32_e32 v146, v146, v201
	v_add_f32_e32 v146, v146, v202
	s_waitcnt lgkmcnt(5)
	v_mfma_f32_32x32x16_bf16 v[18:33], v[106:109], v[86:89], v[18:33]
	v_add_f32_e32 v146, v146, v203
	v_add_f32_e32 v146, v146, v204
	v_add_f32_e32 v146, v146, v205
	v_add_f32_e32 v146, v146, v206
	s_waitcnt lgkmcnt(4)
	v_mfma_f32_32x32x16_bf16 v[2:17], v[110:113], v[86:89], v[2:17]
	v_add_f32_e32 v146, v146, v207
	v_add_f32_e32 v146, v146, v208
	v_add_f32_e32 v146, v146, v209
	v_add_f32_e32 v146, v146, v210
	s_setprio 0
	ds_read_b128 v[130:133], v165 offset:9248
	ds_read_b128 v[138:141], v165 offset:13856
	s_cmp_lg_u32 s24, 4
	s_cselect_b32 s24, s26, 0
	s_waitcnt lgkmcnt(2)
	v_mfma_f32_32x32x16_bf16 v[98:113], v[240:243], v[158:161], v[34:49]
	v_exp_f32_e32 v142, v66
	v_exp_f32_e32 v143, v67
	v_exp_f32_e32 v144, v68
	v_exp_f32_e32 v145, v69
	v_exp_f32_e32 v147, v70
	v_exp_f32_e32 v148, v71
	v_exp_f32_e32 v149, v72
	v_exp_f32_e32 v150, v73
	s_waitcnt lgkmcnt(1)
	v_mfma_f32_32x32x16_bf16 v[82:97], v[244:247], v[158:161], v[34:49]
	v_exp_f32_e32 v151, v74
	v_exp_f32_e32 v152, v75
	v_exp_f32_e32 v153, v76
	v_exp_f32_e32 v178, v77
	v_exp_f32_e32 v134, v78
	v_exp_f32_e32 v135, v79
	v_exp_f32_e32 v136, v80
	v_exp_f32_e32 v137, v81
	v_mfma_f32_32x32x16_bf16 v[98:113], v[130:133], v[154:157], v[98:113]
	v_exp_f32_e32 v179, v50
	v_exp_f32_e32 v185, v51
	v_exp_f32_e32 v186, v52
	v_exp_f32_e32 v187, v53
	v_exp_f32_e32 v194, v54
	v_exp_f32_e32 v195, v55
	v_exp_f32_e32 v196, v56
	v_exp_f32_e32 v197, v57
	s_waitcnt lgkmcnt(0)
	v_mfma_f32_32x32x16_bf16 v[82:97], v[138:141], v[154:157], v[82:97]
	v_exp_f32_e32 v198, v58
	v_exp_f32_e32 v199, v59
	v_exp_f32_e32 v200, v60
	v_exp_f32_e32 v201, v61
	v_exp_f32_e32 v138, v62
	v_exp_f32_e32 v139, v63
	v_exp_f32_e32 v140, v64
	v_exp_f32_e32 v141, v65
	s_cmp_gt_i32 s24, 2
	s_cselect_b32 s25, -3, 2
	s_add_i32 s25, s25, s24
	s_mulk_i32 s25, 0x2400
	v_add_u32_e32 v50, s25, v182
	s_add_i32 s25, s24, 1
	s_cmp_lg_u32 s24, 4
	s_cselect_b32 s25, s25, 0
	s_add_i32 s24, s23, -3
	s_min_u32 s26, s24, s13
	s_lshl_b32 s92, s26, 13
	s_waitcnt vmcnt(3)
	ds_write_b128 v182, v[118:121] offset:27648
	s_waitcnt vmcnt(2)
	ds_write_b128 v50, v[114:117] offset:36864
	s_add_u32 vcc_lo, s100, s92
	s_addc_u32 vcc_hi, s101, 0
	global_load_dwordx4 v[118:121], v248, vcc
	s_add_i32 s92, s23, -4
	s_lshl_b32 s92, s92, 7
	s_add_u32 vcc_lo, s98, s92
	s_addc_u32 vcc_hi, s99, 0
	global_load_dwordx4 v[114:117], v249, vcc
	s_mul_i32 s27, s25, 0x2400
	s_add_i32 s28, s27, 0xffffdc00
	s_cmp_lg_u32 s25, 0
	s_cselect_b32 s28, s28, 0x9000
	v_add_u32_e32 v78, s28, v163
	ds_read_b128 v[50:53], v78 offset:36864
	ds_read_b128 v[54:57], v78 offset:36896
	ds_read_b128 v[58:61], v78 offset:41472
	ds_read_b128 v[62:65], v78 offset:41504
	ds_read_b128 v[66:69], v78 offset:36928
	ds_read_b128 v[70:73], v78 offset:36960
	ds_read_b128 v[74:77], v78 offset:41536
	ds_read_b128 v[78:81], v78 offset:41568
	s_setprio 3
	v_cvt_pk_bf16_f32 v130, v142, v143
	v_cvt_pk_bf16_f32 v131, v144, v145
	v_cvt_pk_bf16_f32 v132, v147, v148
	v_cvt_pk_bf16_f32 v133, v149, v150
	s_waitcnt lgkmcnt(7)
	s_nop 0
	v_mfma_f32_32x32x16_bf16 v[18:33], v[50:53], v[130:133], v[18:33]
	v_add_f32_e32 v176, v142, v143
	v_add_f32_e32 v176, v176, v144
	v_add_f32_e32 v176, v176, v145
	s_waitcnt lgkmcnt(5)
	v_mfma_f32_32x32x16_bf16 v[2:17], v[58:61], v[130:133], v[2:17]
	v_cvt_pk_bf16_f32 v50, v151, v152
	v_cvt_pk_bf16_f32 v51, v153, v178
	v_cvt_pk_bf16_f32 v52, v134, v135
	v_cvt_pk_bf16_f32 v53, v136, v137
	v_add_f32_e32 v176, v176, v147
	v_add_f32_e32 v176, v176, v148
	v_add_f32_e32 v176, v176, v149
	v_add_f32_e32 v176, v176, v150
	s_nop 0
	v_mfma_f32_32x32x16_bf16 v[18:33], v[54:57], v[50:53], v[18:33]
	v_add_f32_e32 v176, v176, v151
	v_add_f32_e32 v176, v176, v152
	v_add_f32_e32 v176, v176, v153
	v_add_f32_e32 v176, v176, v178
	s_waitcnt lgkmcnt(4)
	v_mfma_f32_32x32x16_bf16 v[2:17], v[62:65], v[50:53], v[2:17]
	v_cvt_pk_bf16_f32 v54, v179, v185
	v_cvt_pk_bf16_f32 v55, v186, v187
	v_cvt_pk_bf16_f32 v56, v194, v195
	v_cvt_pk_bf16_f32 v57, v196, v197
	v_add_f32_e32 v176, v176, v134
	v_add_f32_e32 v176, v176, v135
	v_add_f32_e32 v176, v176, v136
	v_add_f32_e32 v176, v176, v137
	s_waitcnt lgkmcnt(3)
	v_mfma_f32_32x32x16_bf16 v[18:33], v[66:69], v[54:57], v[18:33]
	v_add_f32_e32 v176, v176, v179
	v_add_f32_e32 v176, v176, v185
	v_add_f32_e32 v176, v176, v186
	v_add_f32_e32 v176, v176, v187
	s_waitcnt lgkmcnt(1)
	v_mfma_f32_32x32x16_bf16 v[2:17], v[74:77], v[54:57], v[2:17]
	v_cvt_pk_bf16_f32 v50, v198, v199
	v_cvt_pk_bf16_f32 v51, v200, v201
	v_cvt_pk_bf16_f32 v52, v138, v139
	v_cvt_pk_bf16_f32 v53, v140, v141
	v_add_f32_e32 v176, v176, v194
	v_add_f32_e32 v176, v176, v195
	v_add_f32_e32 v176, v176, v196
	v_add_f32_e32 v176, v176, v197
	s_nop 0
	v_mfma_f32_32x32x16_bf16 v[18:33], v[70:73], v[50:53], v[18:33]
	v_add_f32_e32 v176, v176, v198
	v_add_f32_e32 v176, v176, v199
	v_add_f32_e32 v176, v176, v200
	v_add_f32_e32 v176, v176, v201
	s_waitcnt lgkmcnt(0)
	v_mfma_f32_32x32x16_bf16 v[2:17], v[78:81], v[50:53], v[2:17]
	v_add_f32_e32 v176, v176, v138
	v_add_f32_e32 v176, v176, v139
	v_add_f32_e32 v176, v176, v140
	v_add_f32_e32 v176, v176, v141
	s_setprio 2
	s_waitcnt lgkmcnt(0)
	s_barrier
	ds_read_b128 v[240:243], v165 offset:18432
	ds_read_b128 v[244:247], v165 offset:23040
	ds_read_b128 v[134:137], v165 offset:18464
	ds_read_b128 v[138:141], v165 offset:23072
	v_add_f32_e32 v1, v1, v146
	v_exp_f32_e32 v142, v98
	v_exp_f32_e32 v143, v99
	v_exp_f32_e32 v144, v100
	v_exp_f32_e32 v145, v101
	v_exp_f32_e32 v146, v102
	v_exp_f32_e32 v147, v103
	v_exp_f32_e32 v148, v104
	v_exp_f32_e32 v149, v105
	s_waitcnt lgkmcnt(2)
	v_mfma_f32_32x32x16_bf16 v[66:81], v[240:243], v[158:161], v[34:49]
	v_mfma_f32_32x32x16_bf16 v[50:65], v[244:247], v[158:161], v[34:49]
	v_exp_f32_e32 v150, v106
	v_exp_f32_e32 v151, v107
	v_exp_f32_e32 v152, v108
	v_exp_f32_e32 v153, v109
	v_exp_f32_e32 v177, v110
	v_exp_f32_e32 v178, v111
	v_exp_f32_e32 v179, v112
	v_exp_f32_e32 v185, v113
	s_waitcnt lgkmcnt(1)
	v_mfma_f32_32x32x16_bf16 v[66:81], v[134:137], v[154:157], v[66:81]
	v_exp_f32_e32 v186, v82
	v_exp_f32_e32 v187, v83
	v_exp_f32_e32 v194, v84
	v_exp_f32_e32 v195, v85
	v_exp_f32_e32 v134, v86
	v_exp_f32_e32 v135, v87
	v_exp_f32_e32 v136, v88
	v_exp_f32_e32 v137, v89
	s_waitcnt lgkmcnt(0)
	v_mfma_f32_32x32x16_bf16 v[50:65], v[138:141], v[154:157], v[50:65]
	v_exp_f32_e32 v196, v90
	v_exp_f32_e32 v197, v91
	v_exp_f32_e32 v198, v92
	v_exp_f32_e32 v199, v93
	v_exp_f32_e32 v138, v94
	v_exp_f32_e32 v139, v95
	v_exp_f32_e32 v140, v96
	v_exp_f32_e32 v141, v97
	s_cmp_gt_i32 s25, 2
	s_cselect_b32 s28, -3, 2
	s_waitcnt vmcnt(3)
	ds_write_b128 v182, v[126:129]
	s_add_i32 s28, s28, s25
	v_add_u32_e32 v126, s27, v163
	s_add_i32 s27, s23, -2
	s_mulk_i32 s28, 0x2400
	s_min_u32 s27, s27, s13
	v_add_u32_e32 v82, s28, v182
	s_lshl_b32 s92, s27, 13
	s_waitcnt vmcnt(2)
	ds_write_b128 v82, v[122:125] offset:36864
	ds_read_b128 v[82:85], v126 offset:41472
	ds_read_b128 v[86:89], v126 offset:36864
	ds_read_b128 v[90:93], v126 offset:36896
	ds_read_b128 v[94:97], v126 offset:41504
	ds_read_b128 v[106:109], v126 offset:36928
	ds_read_b128 v[110:113], v126 offset:41536
	ds_read_b128 v[122:125], v126 offset:36960
	ds_read_b128 v[126:129], v126 offset:41568
	ds_read_b128 v[240:243], v165 offset:27648
	ds_read_b128 v[244:247], v165 offset:32256
	s_add_u32 vcc_lo, s100, s92
	s_addc_u32 vcc_hi, s101, 0
	global_load_dwordx4 v[98:101], v248, vcc
	s_lshl_b32 s92, s26, 7
	s_add_u32 vcc_lo, s98, s92
	s_addc_u32 vcc_hi, s99, 0
	global_load_dwordx4 v[102:105], v249, vcc
	v_add_f32_e32 v1, v1, v176
	s_add_i32 s28, s25, 1
	s_setprio 1
	v_cvt_pk_bf16_f32 v130, v142, v143
	v_cvt_pk_bf16_f32 v131, v144, v145
	v_cvt_pk_bf16_f32 v132, v146, v147
	v_cvt_pk_bf16_f32 v133, v148, v149
	s_waitcnt lgkmcnt(8)
	s_nop 0
	v_mfma_f32_32x32x16_bf16 v[18:33], v[86:89], v[130:133], v[18:33]
	v_add_f32_e32 v176, v142, v143
	v_add_f32_e32 v176, v176, v144
	v_add_f32_e32 v176, v176, v145
	s_nop 0
	v_mfma_f32_32x32x16_bf16 v[2:17], v[82:85], v[130:133], v[2:17]
	v_cvt_pk_bf16_f32 v86, v150, v151
	v_cvt_pk_bf16_f32 v87, v152, v153
	v_cvt_pk_bf16_f32 v88, v177, v178
	v_cvt_pk_bf16_f32 v89, v179, v185
	v_add_f32_e32 v176, v176, v146
	v_add_f32_e32 v176, v176, v147
	v_add_f32_e32 v176, v176, v148
	v_add_f32_e32 v176, v176, v149
	s_waitcnt lgkmcnt(7)
	v_mfma_f32_32x32x16_bf16 v[18:33], v[90:93], v[86:89], v[18:33]
	v_add_f32_e32 v176, v176, v150
	v_add_f32_e32 v176, v176, v151
	v_add_f32_e32 v176, v176, v152
	v_add_f32_e32 v176, v176, v153
	s_waitcnt lgkmcnt(6)
	v_mfma_f32_32x32x16_bf16 v[2:17], v[94:97], v[86:89], v[2:17]
	v_cvt_pk_bf16_f32 v82, v186, v187
	v_cvt_pk_bf16_f32 v83, v194, v195
	v_cvt_pk_bf16_f32 v84, v134, v135
	v_cvt_pk_bf16_f32 v85, v136, v137
	v_add_f32_e32 v176, v176, v177
	v_add_f32_e32 v176, v176, v178
	v_add_f32_e32 v176, v176, v179
	v_add_f32_e32 v176, v176, v185
	s_waitcnt lgkmcnt(5)
	v_mfma_f32_32x32x16_bf16 v[18:33], v[106:109], v[82:85], v[18:33]
	v_add_f32_e32 v176, v176, v186
	v_add_f32_e32 v176, v176, v187
	v_add_f32_e32 v176, v176, v194
	v_add_f32_e32 v176, v176, v195
	s_waitcnt lgkmcnt(4)
	v_mfma_f32_32x32x16_bf16 v[2:17], v[110:113], v[82:85], v[2:17]
	v_cvt_pk_bf16_f32 v86, v196, v197
	v_cvt_pk_bf16_f32 v87, v198, v199
	v_cvt_pk_bf16_f32 v88, v138, v139
	v_cvt_pk_bf16_f32 v89, v140, v141
	v_add_f32_e32 v176, v176, v134
	v_add_f32_e32 v176, v176, v135
	v_add_f32_e32 v176, v176, v136
	v_add_f32_e32 v176, v176, v137
	s_waitcnt lgkmcnt(3)
	v_mfma_f32_32x32x16_bf16 v[18:33], v[122:125], v[86:89], v[18:33]
	v_add_f32_e32 v176, v176, v196
	v_add_f32_e32 v176, v176, v197
	v_add_f32_e32 v176, v176, v198
	v_add_f32_e32 v176, v176, v199
	s_waitcnt lgkmcnt(2)
	v_mfma_f32_32x32x16_bf16 v[2:17], v[126:129], v[86:89], v[2:17]
	v_add_f32_e32 v176, v176, v138
	v_add_f32_e32 v176, v176, v139
	v_add_f32_e32 v176, v176, v140
	v_add_f32_e32 v176, v176, v141
	s_setprio 0
	ds_read_b128 v[106:109], v165 offset:27680
	ds_read_b128 v[122:125], v165 offset:32288
	s_cmp_lg_u32 s25, 4
	s_cselect_b32 s25, s28, 0
	s_waitcnt lgkmcnt(2)
	v_mfma_f32_32x32x16_bf16 v[138:153], v[240:243], v[158:161], v[34:49]
	v_exp_f32_e32 v126, v66
	v_exp_f32_e32 v127, v67
	v_exp_f32_e32 v128, v68
	v_exp_f32_e32 v129, v69
	v_exp_f32_e32 v130, v70
	v_exp_f32_e32 v131, v71
	v_exp_f32_e32 v132, v72
	v_exp_f32_e32 v133, v73
	s_waitcnt lgkmcnt(1)
	v_mfma_f32_32x32x16_bf16 v[82:97], v[244:247], v[158:161], v[34:49]
	v_exp_f32_e32 v134, v74
	v_exp_f32_e32 v135, v75
	v_exp_f32_e32 v136, v76
	v_exp_f32_e32 v137, v77
	v_exp_f32_e32 v177, v78
	v_exp_f32_e32 v178, v79
	v_exp_f32_e32 v179, v80
	v_exp_f32_e32 v185, v81
	v_mfma_f32_32x32x16_bf16 v[138:153], v[106:109], v[154:157], v[138:153]
	v_exp_f32_e32 v80, v50
	v_exp_f32_e32 v81, v51
	v_exp_f32_e32 v186, v52
	v_exp_f32_e32 v187, v53
	v_exp_f32_e32 v194, v54
	v_exp_f32_e32 v195, v55
	v_exp_f32_e32 v196, v56
	v_exp_f32_e32 v197, v57
	s_waitcnt lgkmcnt(0)
	v_mfma_f32_32x32x16_bf16 v[82:97], v[122:125], v[154:157], v[82:97]
	v_exp_f32_e32 v198, v58
	v_exp_f32_e32 v199, v59
	v_exp_f32_e32 v200, v60
	v_exp_f32_e32 v201, v61
	v_exp_f32_e32 v122, v62
	v_exp_f32_e32 v123, v63
	v_exp_f32_e32 v124, v64
	v_exp_f32_e32 v125, v65
	s_cmp_gt_i32 s25, 2
	s_cselect_b32 s26, -3, 2
	s_add_i32 s26, s26, s25
	s_mulk_i32 s26, 0x2400
	v_add_u32_e32 v50, s26, v182
	s_add_i32 s26, s25, 1
	s_cmp_lg_u32 s25, 4
	s_cselect_b32 s25, s26, 0
	s_add_i32 s26, s23, -1
	s_min_u32 s26, s26, s13
	s_lshl_b32 s92, s26, 13
	s_waitcnt vmcnt(3)
	ds_write_b128 v182, v[118:121] offset:9216
	s_waitcnt vmcnt(2)
	ds_write_b128 v50, v[114:117] offset:36864
	s_add_u32 vcc_lo, s100, s92
	s_addc_u32 vcc_hi, s101, 0
	global_load_dwordx4 v[56:59], v248, vcc
	s_lshl_b32 s92, s27, 7
	s_add_u32 vcc_lo, s98, s92
	s_addc_u32 vcc_hi, s99, 0
	global_load_dwordx4 v[52:55], v249, vcc
	s_nop 0
	s_mul_i32 s27, s25, 0x2400
	s_add_i32 s28, s27, 0xffffdc00
	s_cmp_lg_u32 s25, 0
	s_cselect_b32 s28, s28, 0x9000
	v_add_u32_e32 v50, s28, v163
	ds_read_b128 v[60:63], v50 offset:36864
	ds_read_b128 v[64:67], v50 offset:36896
	ds_read_b128 v[68:71], v50 offset:41472
	ds_read_b128 v[72:75], v50 offset:41504
	ds_read_b128 v[76:79], v50 offset:36928
	ds_read_b128 v[106:109], v50 offset:36960
	ds_read_b128 v[110:113], v50 offset:41536
	ds_read_b128 v[114:117], v50 offset:41568
	s_setprio 3
	v_cvt_pk_bf16_f32 v118, v126, v127
	v_cvt_pk_bf16_f32 v119, v128, v129
	v_cvt_pk_bf16_f32 v120, v130, v131
	v_cvt_pk_bf16_f32 v121, v132, v133
	s_waitcnt lgkmcnt(7)
	s_nop 0
	v_mfma_f32_32x32x16_bf16 v[18:33], v[60:63], v[118:121], v[18:33]
	v_add_f32_e32 v50, v126, v127
	v_add_f32_e32 v50, v50, v128
	v_add_f32_e32 v50, v50, v129
	s_waitcnt lgkmcnt(5)
	v_mfma_f32_32x32x16_bf16 v[2:17], v[68:71], v[118:121], v[2:17]
	v_cvt_pk_bf16_f32 v60, v134, v135
	v_cvt_pk_bf16_f32 v61, v136, v137
	v_cvt_pk_bf16_f32 v62, v177, v178
	v_cvt_pk_bf16_f32 v63, v179, v185
	v_add_f32_e32 v50, v50, v130
	v_add_f32_e32 v50, v50, v131
	v_add_f32_e32 v50, v50, v132
	v_add_f32_e32 v50, v50, v133
	s_nop 0
	v_mfma_f32_32x32x16_bf16 v[18:33], v[64:67], v[60:63], v[18:33]
	v_add_f32_e32 v50, v50, v134
	v_add_f32_e32 v50, v50, v135
	v_add_f32_e32 v50, v50, v136
	v_add_f32_e32 v50, v50, v137
	s_waitcnt lgkmcnt(4)
	v_mfma_f32_32x32x16_bf16 v[2:17], v[72:75], v[60:63], v[2:17]
	v_cvt_pk_bf16_f32 v64, v80, v81
	v_cvt_pk_bf16_f32 v65, v186, v187
	v_cvt_pk_bf16_f32 v66, v194, v195
	v_cvt_pk_bf16_f32 v67, v196, v197
	v_add_f32_e32 v50, v50, v177
	v_add_f32_e32 v50, v50, v178
	v_add_f32_e32 v50, v50, v179
	v_add_f32_e32 v50, v50, v185
	s_waitcnt lgkmcnt(3)
	v_mfma_f32_32x32x16_bf16 v[18:33], v[76:79], v[64:67], v[18:33]
	v_add_f32_e32 v50, v50, v80
	v_add_f32_e32 v50, v50, v81
	v_add_f32_e32 v50, v50, v186
	v_add_f32_e32 v50, v50, v187
	s_waitcnt lgkmcnt(1)
	v_mfma_f32_32x32x16_bf16 v[2:17], v[110:113], v[64:67], v[2:17]
	v_cvt_pk_bf16_f32 v60, v198, v199
	v_cvt_pk_bf16_f32 v61, v200, v201
	v_cvt_pk_bf16_f32 v62, v122, v123
	v_cvt_pk_bf16_f32 v63, v124, v125
	v_add_f32_e32 v50, v50, v194
	v_add_f32_e32 v50, v50, v195
	v_add_f32_e32 v50, v50, v196
	v_add_f32_e32 v50, v50, v197
	s_nop 0
	v_mfma_f32_32x32x16_bf16 v[18:33], v[106:109], v[60:63], v[18:33]
	v_add_f32_e32 v50, v50, v198
	v_add_f32_e32 v50, v50, v199
	v_add_f32_e32 v50, v50, v200
	v_add_f32_e32 v50, v50, v201
	s_waitcnt lgkmcnt(0)
	v_mfma_f32_32x32x16_bf16 v[2:17], v[114:117], v[60:63], v[2:17]
	v_add_f32_e32 v50, v50, v122
	v_add_f32_e32 v50, v50, v123
	v_add_f32_e32 v50, v50, v124
	v_add_f32_e32 v50, v50, v125
	s_setprio 2
	s_waitcnt lgkmcnt(0)
	s_barrier
	ds_read_b128 v[240:243], v165
	ds_read_b128 v[244:247], v165 offset:4608
	ds_read_b128 v[68:71], v165 offset:32
	ds_read_b128 v[72:75], v165 offset:4640
	v_add_f32_e32 v1, v1, v176
	v_exp_f32_e32 v176, v138
	v_exp_f32_e32 v177, v139
	v_exp_f32_e32 v178, v140
	v_exp_f32_e32 v179, v141
	v_exp_f32_e32 v185, v142
	v_exp_f32_e32 v186, v143
	v_exp_f32_e32 v187, v144
	v_exp_f32_e32 v194, v145
	s_waitcnt lgkmcnt(2)
	v_mfma_f32_32x32x16_bf16 v[122:137], v[240:243], v[158:161], v[34:49]
	v_mfma_f32_32x32x16_bf16 v[106:121], v[244:247], v[158:161], v[34:49]
	v_exp_f32_e32 v195, v146
	v_exp_f32_e32 v196, v147
	v_exp_f32_e32 v197, v148
	v_exp_f32_e32 v198, v149
	v_exp_f32_e32 v146, v150
	v_exp_f32_e32 v147, v151
	v_exp_f32_e32 v148, v152
	v_exp_f32_e32 v149, v153
	s_waitcnt lgkmcnt(1)
	v_mfma_f32_32x32x16_bf16 v[122:137], v[68:71], v[154:157], v[122:137]
	v_exp_f32_e32 v150, v82
	v_exp_f32_e32 v151, v83
	v_exp_f32_e32 v152, v84
	v_exp_f32_e32 v153, v85
	v_exp_f32_e32 v199, v86
	v_exp_f32_e32 v200, v87
	v_exp_f32_e32 v201, v88
	v_exp_f32_e32 v202, v89
	s_waitcnt lgkmcnt(0)
	v_mfma_f32_32x32x16_bf16 v[106:121], v[72:75], v[154:157], v[106:121]
	v_exp_f32_e32 v203, v90
	v_exp_f32_e32 v204, v91
	v_exp_f32_e32 v205, v92
	v_exp_f32_e32 v206, v93
	v_exp_f32_e32 v207, v94
	v_exp_f32_e32 v208, v95
	v_exp_f32_e32 v209, v96
	v_exp_f32_e32 v210, v97
	v_add_u32_e32 v88, s27, v163
	ds_read_b128 v[60:63], v88 offset:41472
	ds_read_b128 v[64:67], v88 offset:36864
	ds_read_b128 v[68:71], v88 offset:36896
	ds_read_b128 v[72:75], v88 offset:41504
	ds_read_b128 v[76:79], v88 offset:36928
	ds_read_b128 v[80:83], v88 offset:41536
	ds_read_b128 v[84:87], v88 offset:36960
	ds_read_b128 v[88:91], v88 offset:41568
	ds_read_b128 v[240:243], v165 offset:9216
	ds_read_b128 v[244:247], v165 offset:13824
	s_cmp_gt_i32 s25, 2
	s_cselect_b32 s28, -3, 2
	s_add_i32 s28, s28, s25
	s_mulk_i32 s28, 0x2400
	s_min_u32 s27, s23, s13
	v_add_u32_e32 v51, s28, v182
	s_lshl_b32 s92, s27, 13
	s_waitcnt vmcnt(3)
	ds_write_b128 v182, v[98:101] offset:18432
	s_waitcnt vmcnt(2)
	ds_write_b128 v51, v[102:105] offset:36864
	v_add_f32_e32 v1, v1, v50
	s_add_u32 vcc_lo, s100, s92
	s_addc_u32 vcc_hi, s101, 0
	global_load_dwordx4 v[138:141], v248, vcc
	s_lshl_b32 s92, s26, 7
	s_add_u32 vcc_lo, s98, s92
	s_addc_u32 vcc_hi, s99, 0
	global_load_dwordx4 v[142:145], v249, vcc
	s_setprio 1
	v_mov_b32_e32 v51, v122
	v_cvt_pk_bf16_f32 v92, v176, v177
	v_cvt_pk_bf16_f32 v93, v178, v179
	v_cvt_pk_bf16_f32 v94, v185, v186
	v_cvt_pk_bf16_f32 v95, v187, v194
	s_waitcnt lgkmcnt(10)
	s_nop 0
	v_mfma_f32_32x32x16_bf16 v[18:33], v[64:67], v[92:95], v[18:33]
	v_max3_f32 v51, v51, v123, v124
	v_max3_f32 v51, v51, v125, v126
	v_add_f32_e32 v50, v176, v177
	v_add_f32_e32 v50, v50, v178
	v_add_f32_e32 v50, v50, v179
	s_nop 0
	v_mfma_f32_32x32x16_bf16 v[2:17], v[60:63], v[92:95], v[2:17]
	v_cvt_pk_bf16_f32 v64, v195, v196
	v_cvt_pk_bf16_f32 v65, v197, v198
	v_cvt_pk_bf16_f32 v66, v146, v147
	v_cvt_pk_bf16_f32 v67, v148, v149
	v_max3_f32 v51, v51, v127, v128
	v_max3_f32 v51, v51, v129, v130
	v_add_f32_e32 v50, v50, v185
	v_add_f32_e32 v50, v50, v186
	v_add_f32_e32 v50, v50, v187
	v_add_f32_e32 v50, v50, v194
	s_waitcnt lgkmcnt(9)
	v_mfma_f32_32x32x16_bf16 v[18:33], v[68:71], v[64:67], v[18:33]
	v_max3_f32 v51, v51, v131, v132
	v_max3_f32 v51, v51, v133, v134
	v_add_f32_e32 v50, v50, v195
	v_add_f32_e32 v50, v50, v196
	v_add_f32_e32 v50, v50, v197
	v_add_f32_e32 v50, v50, v198
	s_waitcnt lgkmcnt(8)
	v_mfma_f32_32x32x16_bf16 v[2:17], v[72:75], v[64:67], v[2:17]
	v_cvt_pk_bf16_f32 v60, v150, v151
	v_cvt_pk_bf16_f32 v61, v152, v153
	v_cvt_pk_bf16_f32 v62, v199, v200
	v_cvt_pk_bf16_f32 v63, v201, v202
	v_max3_f32 v51, v51, v135, v136
	v_max3_f32 v51, v51, v137, v106
	v_add_f32_e32 v50, v50, v146
	v_add_f32_e32 v50, v50, v147
	v_add_f32_e32 v50, v50, v148
	v_add_f32_e32 v50, v50, v149
	s_waitcnt lgkmcnt(7)
	v_mfma_f32_32x32x16_bf16 v[18:33], v[76:79], v[60:63], v[18:33]
	v_max3_f32 v51, v51, v107, v108
	v_max3_f32 v51, v51, v109, v110
	v_add_f32_e32 v50, v50, v150
	v_add_f32_e32 v50, v50, v151
	v_add_f32_e32 v50, v50, v152
	v_add_f32_e32 v50, v50, v153
	s_waitcnt lgkmcnt(6)
	v_mfma_f32_32x32x16_bf16 v[2:17], v[80:83], v[60:63], v[2:17]
	v_cvt_pk_bf16_f32 v64, v203, v204
	v_cvt_pk_bf16_f32 v65, v205, v206
	v_cvt_pk_bf16_f32 v66, v207, v208
	v_cvt_pk_bf16_f32 v67, v209, v210
	v_max3_f32 v51, v51, v111, v112
	v_max3_f32 v51, v51, v113, v114
	v_add_f32_e32 v50, v50, v199
	v_add_f32_e32 v50, v50, v200
	v_add_f32_e32 v50, v50, v201
	v_add_f32_e32 v50, v50, v202
	s_waitcnt lgkmcnt(5)
	v_mfma_f32_32x32x16_bf16 v[18:33], v[84:87], v[64:67], v[18:33]
	v_max3_f32 v51, v51, v115, v116
	v_max3_f32 v51, v51, v117, v118
	v_add_f32_e32 v50, v50, v203
	v_add_f32_e32 v50, v50, v204
	v_add_f32_e32 v50, v50, v205
	v_add_f32_e32 v50, v50, v206
	s_waitcnt lgkmcnt(4)
	v_mfma_f32_32x32x16_bf16 v[2:17], v[88:91], v[64:67], v[2:17]
	v_max3_f32 v51, v51, v119, v120
	v_max3_f32 v51, v51, v121, v121
	v_add_f32_e32 v50, v50, v207
	v_add_f32_e32 v50, v50, v208
	v_add_f32_e32 v50, v50, v209
	v_add_f32_e32 v50, v50, v210
	s_setprio 0
	ds_read_b128 v[146:149], v165 offset:9248
	ds_read_b128 v[60:63], v165 offset:13856
	v_add_f32_e32 v50, v1, v50
	v_mov_b32_e32 v1, v51
	s_nop 1
	v_permlane32_swap_b32_e32 v51, v1
	v_max_f32_e32 v1, v51, v1
	v_cmp_lt_f32_e32 vcc, s52, v1
	s_cbranch_vccz .LBB0_643
	v_max_f32_e32 v1, v1, v1
	v_max_f32_e32 v68, 0, v1
	v_add_f32_e32 v183, v183, v68
	v_xor_b32_e32 v34, 0x80000000, v183
	v_pk_add_f32 v[122:123], v[122:123], v[68:69] op_sel_hi:[1,0] neg_lo:[0,1] neg_hi:[0,1]
	v_pk_add_f32 v[106:107], v[106:107], v[68:69] op_sel_hi:[1,0] neg_lo:[0,1] neg_hi:[0,1]
	v_pk_add_f32 v[124:125], v[124:125], v[68:69] op_sel_hi:[1,0] neg_lo:[0,1] neg_hi:[0,1]
	v_pk_add_f32 v[108:109], v[108:109], v[68:69] op_sel_hi:[1,0] neg_lo:[0,1] neg_hi:[0,1]
	v_pk_add_f32 v[126:127], v[126:127], v[68:69] op_sel_hi:[1,0] neg_lo:[0,1] neg_hi:[0,1]
	v_pk_add_f32 v[110:111], v[110:111], v[68:69] op_sel_hi:[1,0] neg_lo:[0,1] neg_hi:[0,1]
	v_pk_add_f32 v[128:129], v[128:129], v[68:69] op_sel_hi:[1,0] neg_lo:[0,1] neg_hi:[0,1]
	v_pk_add_f32 v[112:113], v[112:113], v[68:69] op_sel_hi:[1,0] neg_lo:[0,1] neg_hi:[0,1]
	v_pk_add_f32 v[130:131], v[130:131], v[68:69] op_sel_hi:[1,0] neg_lo:[0,1] neg_hi:[0,1]
	v_pk_add_f32 v[114:115], v[114:115], v[68:69] op_sel_hi:[1,0] neg_lo:[0,1] neg_hi:[0,1]
	v_pk_add_f32 v[132:133], v[132:133], v[68:69] op_sel_hi:[1,0] neg_lo:[0,1] neg_hi:[0,1]
	v_pk_add_f32 v[116:117], v[116:117], v[68:69] op_sel_hi:[1,0] neg_lo:[0,1] neg_hi:[0,1]
	v_pk_add_f32 v[134:135], v[134:135], v[68:69] op_sel_hi:[1,0] neg_lo:[0,1] neg_hi:[0,1]
	v_pk_add_f32 v[118:119], v[118:119], v[68:69] op_sel_hi:[1,0] neg_lo:[0,1] neg_hi:[0,1]
	v_pk_add_f32 v[136:137], v[136:137], v[68:69] op_sel_hi:[1,0] neg_lo:[0,1] neg_hi:[0,1]
	v_pk_add_f32 v[120:121], v[120:121], v[68:69] op_sel_hi:[1,0] neg_lo:[0,1] neg_hi:[0,1]
	v_exp_f32_e64 v68, -v68
	v_mov_b32_e32 v35, v34
	v_mov_b32_e32 v36, v34
	v_mov_b32_e32 v37, v34
	v_mov_b32_e32 v38, v34
	v_mov_b32_e32 v39, v34
	v_mov_b32_e32 v40, v34
	v_mov_b32_e32 v41, v34
	v_mov_b32_e32 v42, v34
	v_mov_b32_e32 v43, v34
	v_mov_b32_e32 v44, v34
	v_mov_b32_e32 v45, v34
	v_mov_b32_e32 v46, v34
	v_mov_b32_e32 v47, v34
	v_mov_b32_e32 v48, v34
	v_mov_b32_e32 v49, v34
	s_nop 11
	v_pk_mul_f32 v[32:33], v[32:33], v[68:69] op_sel_hi:[1,0]
	v_pk_mul_f32 v[30:31], v[30:31], v[68:69] op_sel_hi:[1,0]
	v_pk_mul_f32 v[28:29], v[28:29], v[68:69] op_sel_hi:[1,0]
	v_pk_mul_f32 v[26:27], v[26:27], v[68:69] op_sel_hi:[1,0]
	v_pk_mul_f32 v[24:25], v[24:25], v[68:69] op_sel_hi:[1,0]
	v_pk_mul_f32 v[22:23], v[22:23], v[68:69] op_sel_hi:[1,0]
	v_pk_mul_f32 v[20:21], v[20:21], v[68:69] op_sel_hi:[1,0]
	v_pk_mul_f32 v[18:19], v[18:19], v[68:69] op_sel_hi:[1,0]
	v_pk_mul_f32 v[16:17], v[16:17], v[68:69] op_sel_hi:[1,0]
	v_pk_mul_f32 v[14:15], v[14:15], v[68:69] op_sel_hi:[1,0]
	v_pk_mul_f32 v[12:13], v[12:13], v[68:69] op_sel_hi:[1,0]
	v_pk_mul_f32 v[10:11], v[10:11], v[68:69] op_sel_hi:[1,0]
	v_pk_mul_f32 v[8:9], v[8:9], v[68:69] op_sel_hi:[1,0]
	v_pk_mul_f32 v[6:7], v[6:7], v[68:69] op_sel_hi:[1,0]
	v_pk_mul_f32 v[4:5], v[4:5], v[68:69] op_sel_hi:[1,0]
	v_pk_mul_f32 v[2:3], v[2:3], v[68:69] op_sel_hi:[1,0]
	v_mul_f32_e32 v50, v50, v68
